# v33 + the same leading-half read relaxation in the unrolled K=256 GEMM instance (uq/ukv)
# speedup vs baseline: 1.0040x; 1.0006x over previous
; #define PG8_STAGE(bufoff, gbase, voff) do { _Pragma("unroll") for (int _i = 0; _i < 2; ++_i) \
;         __builtin_amdgcn_global_load_lds((const unsigned*)((const char*)(gbase) + (voff)[_i]), (LAS unsigned*)(lds + (bufoff) + ldsw + _i * 8192), 16, 0, 0); } while (0)
; #define PG8_LDA(dst, b, h) do { _Pragma("unroll") for (int m = 0; m < 4; ++m) _Pragma("unroll") for (int k = 0; k < 2; ++k) dst[m][k] = *(const LAS bf16x8*)(lds + PG8_SA(b, h) + aoff + m * 2048 + k * 1024); } while (0)
; #define PG8_LDB(dst, b, h) do { _Pragma("unroll") for (int n = 0; n < 2; ++n) _Pragma("unroll") for (int k = 0; k < 2; ++k) dst[n][k] = *(const LAS bf16x8*)(lds + PG8_SB(b, h) + boff + n * 2048 + k * 1024); } while (0)
; #define PG8_MMA(ai, bj, At, Bt) do { __builtin_amdgcn_s_setprio(1); _Pragma("unroll") for (int m = 0; m < 4; ++m) _Pragma("unroll") for (int n = 0; n < 2; ++n) _Pragma("unroll") for (int k = 0; k < 2; ++k) \
;         acc[ai][bj][m][n] = __builtin_amdgcn_mfma_f32_16x16x32_bf16(Bt[n][k], At[m][k], acc[ai][bj][m][n], 0, 0, 0); __builtin_amdgcn_s_setprio(0); } while (0)
; #define PG8_BAR __builtin_amdgcn_s_barrier()
; template <class Epi>
; __device__ __forceinline__ void gemm_phase(LAS unsigned char* lds, const Gemm g, const StaticOrder& S, const Epi& E, int wave_s) {
;     ...
;         const bool has_next = S.next(ui + 1, nxt);
;         const char* nA = has_next ? (const char*)g.A + (size_t)nxt.pm * tstepA : cA; const char* nB = has_next ? (const char*)g.Bt + (size_t)nxt.pn * tstepB : cB;
;         for (int t = 0; t < nt; t += 2) {
;             const bool last = (t == nt - 2);
;             const char* a1 = cA + (size_t)(t + 1) * kstep;
;             const char* a2 = last ? nA : cA + (size_t)(t + 2) * kstep; const char* b2 = last ? nB : cB + (size_t)(t + 2) * kstep;
;             const char* a3 = a2 + kstep; const char* b3 = b2 + kstep;
;             PG8_LDB(B0, 0, 0); PG8_LDB(B1, 0, 1); PG8_SCHED; PG8_LDA(At, 0, 0); PG8_STAGE(PG8_SA(1, 1), a1 + hstepA, voffA);
;             PG8_WAIT_V(8); PG8_WAIT_L(0); PG8_BAR; PG8_MMA(0, 0, At, B0); PG8_MMA(0, 1, At, B1); PG8_BAR; PG8_SCHED;
;             PG8_LDA(At, 0, 1); PG8_STAGE(PG8_SB(0, 0), b2, voffB); PG8_STAGE(PG8_SB(0, 1), b2 + hstepB, voffB); PG8_STAGE(PG8_SA(0, 0), a2, voffA);
;             PG8_WAIT_V(8); PG8_WAIT_L(0); PG8_BAR; PG8_MMA(1, 0, At, B0); PG8_MMA(1, 1, At, B1); PG8_BAR; PG8_SCHED;
.LBB0_464:
	s_ashr_i32 s11, s10, 31
	s_lshl_b64 s[16:17], s[10:11], 17
	s_add_u32 s16, s25, s16
	s_addc_u32 s17, s29, s17
	s_and_b64 s[2:3], s[2:3], exec
	s_cselect_b32 s3, s17, s23
	s_cselect_b32 s2, s16, s22
	s_add_i32 s45, 0, 0x10000
	s_add_i32 s44, 0, 0x14000
	v_add_u32_e32 v163, s45, v161
	v_add_u32_e32 v218, s44, v161
	ds_read_b128 v[0:3], v163
	ds_read_b128 v[4:7], v163 offset:1024
	ds_read_b128 v[8:11], v163 offset:2048
	ds_read_b128 v[14:17], v163 offset:3072
	ds_read_b128 v[34:37], v162
	ds_read_b128 v[38:41], v162 offset:1024
	ds_read_b128 v[42:45], v162 offset:2048
	ds_read_b128 v[46:49], v162 offset:3072
	ds_read_b128 v[50:53], v162 offset:4096
	ds_read_b128 v[54:57], v162 offset:5120
	ds_read_b128 v[58:61], v162 offset:6144
	ds_read_b128 v[62:65], v162 offset:7168
	ds_read_b128 v[18:21], v218
	ds_read_b128 v[22:25], v218 offset:1024
	ds_read_b128 v[26:29], v218 offset:2048
	ds_read_b128 v[30:33], v218 offset:3072
	s_add_u32 s36, s26, 0xc0080
	s_addc_u32 s37, s27, 0
	s_add_i32 s47, s31, 0xc000
	v_lshl_add_u64 v[66:67], s[36:37], 0, v[152:153]
	s_mov_b32 m0, s47
	s_add_i32 s11, s31, 0xe000
	global_load_lds_dwordx4 v[66:67], off
	v_lshl_add_u64 v[66:67], s[36:37], 0, v[148:149]
	s_mov_b32 m0, s11
	s_nop 0
	global_load_lds_dwordx4 v[66:67], off
	s_waitcnt vmcnt(8)
	s_cmp_lg_u64 s[6:7], 0
	s_cbranch_scc1 .Lpp_lead_1
	s_waitcnt lgkmcnt(0)
.Lpp_lead_1:
	s_waitcnt lgkmcnt(4)
	s_barrier
	s_setprio 1
	s_waitcnt lgkmcnt(4)
	v_mfma_f32_16x16x32_bf16 v[66:69], v[0:3], v[34:37], 0
	v_mfma_f32_16x16x32_bf16 v[70:73], v[8:11], v[34:37], 0
	v_mfma_f32_16x16x32_bf16 v[74:77], v[0:3], v[42:45], 0
	v_mfma_f32_16x16x32_bf16 v[78:81], v[8:11], v[42:45], 0
	v_mfma_f32_16x16x32_bf16 v[82:85], v[0:3], v[50:53], 0
	v_mfma_f32_16x16x32_bf16 v[86:89], v[8:11], v[50:53], 0
	v_mfma_f32_16x16x32_bf16 v[90:93], v[0:3], v[58:61], 0
	v_mfma_f32_16x16x32_bf16 v[94:97], v[8:11], v[58:61], 0
	v_mfma_f32_16x16x32_bf16 v[66:69], v[4:7], v[38:41], v[66:69]
	v_mfma_f32_16x16x32_bf16 v[70:73], v[14:17], v[38:41], v[70:73]
	v_mfma_f32_16x16x32_bf16 v[74:77], v[4:7], v[46:49], v[74:77]
	v_mfma_f32_16x16x32_bf16 v[78:81], v[14:17], v[46:49], v[78:81]
	v_mfma_f32_16x16x32_bf16 v[82:85], v[4:7], v[54:57], v[82:85]
	v_mfma_f32_16x16x32_bf16 v[86:89], v[14:17], v[54:57], v[86:89]
	v_mfma_f32_16x16x32_bf16 v[90:93], v[4:7], v[62:65], v[90:93]
	v_mfma_f32_16x16x32_bf16 v[94:97], v[14:17], v[62:65], v[94:97]
	s_setprio 0
	s_setprio 1
	s_waitcnt lgkmcnt(0)
	v_mfma_f32_16x16x32_bf16 v[98:101], v[18:21], v[34:37], 0
	v_mfma_f32_16x16x32_bf16 v[34:37], v[26:29], v[34:37], 0
	v_mfma_f32_16x16x32_bf16 v[98:101], v[22:25], v[38:41], v[98:101]
	v_mfma_f32_16x16x32_bf16 v[34:37], v[30:33], v[38:41], v[34:37]
	v_mfma_f32_16x16x32_bf16 v[38:41], v[18:21], v[42:45], 0
	v_mfma_f32_16x16x32_bf16 v[42:45], v[26:29], v[42:45], 0
	v_mfma_f32_16x16x32_bf16 v[38:41], v[22:25], v[46:49], v[38:41]
	v_mfma_f32_16x16x32_bf16 v[42:45], v[30:33], v[46:49], v[42:45]
	v_mfma_f32_16x16x32_bf16 v[46:49], v[18:21], v[50:53], 0
	v_mfma_f32_16x16x32_bf16 v[50:53], v[26:29], v[50:53], 0
	v_mfma_f32_16x16x32_bf16 v[46:49], v[22:25], v[54:57], v[46:49]
	v_mfma_f32_16x16x32_bf16 v[50:53], v[30:33], v[54:57], v[50:53]
	v_mfma_f32_16x16x32_bf16 v[54:57], v[18:21], v[58:61], 0
	v_mfma_f32_16x16x32_bf16 v[58:61], v[26:29], v[58:61], 0
	v_mfma_f32_16x16x32_bf16 v[54:57], v[22:25], v[62:65], v[54:57]
	v_mfma_f32_16x16x32_bf16 v[58:61], v[30:33], v[62:65], v[58:61]
	s_setprio 0
	s_barrier
	s_add_i32 s45, s45, s30
	v_lshl_add_u64 v[172:173], s[22:23], 0, v[150:151]
	s_add_i32 s36, s45, 0x2000
	v_lshl_add_u64 v[130:131], v[172:173], 0, s[58:59]
	s_mov_b32 m0, s45
	v_lshl_add_u64 v[174:175], s[22:23], 0, v[146:147]
	s_add_u32 s48, s22, 0x10100
	ds_read_b128 v[62:65], v162 offset:16384
	ds_read_b128 v[102:105], v162 offset:17408
	ds_read_b128 v[106:109], v162 offset:18432
	ds_read_b128 v[110:113], v162 offset:19456
	ds_read_b128 v[114:117], v162 offset:20480
	ds_read_b128 v[118:121], v162 offset:21504
	ds_read_b128 v[122:125], v162 offset:22528
	ds_read_b128 v[126:129], v162 offset:23552
	global_load_lds_dwordx4 v[130:131], off
	v_lshl_add_u64 v[130:131], v[174:175], 0, s[58:59]
	s_mov_b32 m0, s36
	s_addc_u32 s49, s23, 0
	s_add_i32 s37, s44, s30
	global_load_lds_dwordx4 v[130:131], off
	v_lshl_add_u64 v[130:131], s[48:49], 0, v[150:151]
	s_mov_b32 m0, s37
	s_add_i32 s44, s37, 0x2000
	global_load_lds_dwordx4 v[130:131], off
	v_lshl_add_u64 v[130:131], s[48:49], 0, v[146:147]
	s_mov_b32 m0, s44
	v_lshl_add_u64 v[176:177], s[26:27], 0, v[152:153]
	global_load_lds_dwordx4 v[130:131], off
	v_lshl_add_u64 v[130:131], v[176:177], 0, s[58:59]
	s_mov_b32 m0, s31
	v_lshl_add_u64 v[214:215], s[26:27], 0, v[148:149]
	global_load_lds_dwordx4 v[130:131], off
	v_lshl_add_u64 v[130:131], v[214:215], 0, s[58:59]
	s_mov_b32 m0, s40
	s_nop 0
	global_load_lds_dwordx4 v[130:131], off
	s_waitcnt vmcnt(8)
	s_waitcnt lgkmcnt(0)
	s_barrier
; #define PG8_STAGE(bufoff, gbase, voff) do { _Pragma("unroll") for (int _i = 0; _i < 2; ++_i) \
;         __builtin_amdgcn_global_load_lds((const unsigned*)((const char*)(gbase) + (voff)[_i]), (LAS unsigned*)(lds + (bufoff) + ldsw + _i * 8192), 16, 0, 0); } while (0)
; #define PG8_LDA(dst, b, h) do { _Pragma("unroll") for (int m = 0; m < 4; ++m) _Pragma("unroll") for (int k = 0; k < 2; ++k) dst[m][k] = *(const LAS bf16x8*)(lds + PG8_SA(b, h) + aoff + m * 2048 + k * 1024); } while (0)
; #define PG8_LDB(dst, b, h) do { _Pragma("unroll") for (int n = 0; n < 2; ++n) _Pragma("unroll") for (int k = 0; k < 2; ++k) dst[n][k] = *(const LAS bf16x8*)(lds + PG8_SB(b, h) + boff + n * 2048 + k * 1024); } while (0)
; #define PG8_MMA(ai, bj, At, Bt) do { __builtin_amdgcn_s_setprio(1); _Pragma("unroll") for (int m = 0; m < 4; ++m) _Pragma("unroll") for (int n = 0; n < 2; ++n) _Pragma("unroll") for (int k = 0; k < 2; ++k) \
;         acc[ai][bj][m][n] = __builtin_amdgcn_mfma_f32_16x16x32_bf16(Bt[n][k], At[m][k], acc[ai][bj][m][n], 0, 0, 0); __builtin_amdgcn_s_setprio(0); } while (0)
; #define PG8_WAIT_V(n) asm volatile("s_waitcnt vmcnt(" #n ")" ::: "memory")
; #define PG8_WAIT_L(n) asm volatile("s_waitcnt lgkmcnt(" #n ")" ::: "memory")
; #define PG8_BAR __builtin_amdgcn_s_barrier()
; #define PG8_SCHED __builtin_amdgcn_sched_barrier(0)
; template <class Epi>
; __device__ __forceinline__ void gemm_phase(LAS unsigned char* lds, const Gemm g, const StaticOrder& S, const Epi& E, int wave_s) {
;     ...
;             PG8_WAIT_V(8); PG8_WAIT_L(0); PG8_BAR; PG8_MMA(1, 0, At, B0); PG8_MMA(1, 1, At, B1); PG8_BAR; PG8_SCHED;
;             PG8_LDB(B0, 1, 0); PG8_LDB(B1, 1, 1); PG8_SCHED; PG8_LDA(At, 1, 0); PG8_STAGE(PG8_SA(0, 1), a2 + hstepA, voffA);
;             PG8_WAIT_V(8); PG8_WAIT_L(0); PG8_BAR; PG8_MMA(0, 0, At, B0); PG8_MMA(0, 1, At, B1); PG8_BAR; PG8_SCHED;
	s_setprio 1
	s_waitcnt lgkmcnt(0)
	v_mfma_f32_16x16x32_bf16 v[130:133], v[0:3], v[62:65], 0
	v_mfma_f32_16x16x32_bf16 v[138:141], v[0:3], v[106:109], 0
	v_mfma_f32_16x16x32_bf16 v[156:159], v[0:3], v[114:117], 0
	v_mfma_f32_16x16x32_bf16 v[0:3], v[0:3], v[122:125], 0
	v_mfma_f32_16x16x32_bf16 v[130:133], v[4:7], v[102:105], v[130:133]
	v_mfma_f32_16x16x32_bf16 v[138:141], v[4:7], v[110:113], v[138:141]
	v_mfma_f32_16x16x32_bf16 v[156:159], v[4:7], v[118:121], v[156:159]
	v_mfma_f32_16x16x32_bf16 v[0:3], v[4:7], v[126:129], v[0:3]
	v_mfma_f32_16x16x32_bf16 v[4:7], v[8:11], v[122:125], 0
	v_mfma_f32_16x16x32_bf16 v[134:137], v[8:11], v[62:65], 0
	v_mfma_f32_16x16x32_bf16 v[142:145], v[8:11], v[106:109], 0
	v_mfma_f32_16x16x32_bf16 v[164:167], v[8:11], v[114:117], 0
	v_mfma_f32_16x16x32_bf16 v[4:7], v[14:17], v[126:129], v[4:7]
	v_mfma_f32_16x16x32_bf16 v[134:137], v[14:17], v[102:105], v[134:137]
	v_mfma_f32_16x16x32_bf16 v[142:145], v[14:17], v[110:113], v[142:145]
	v_mfma_f32_16x16x32_bf16 v[164:167], v[14:17], v[118:121], v[164:167]
	s_setprio 0
	s_setprio 1
	v_mfma_f32_16x16x32_bf16 v[8:11], v[18:21], v[62:65], 0
	v_mfma_f32_16x16x32_bf16 v[14:17], v[26:29], v[62:65], 0
	v_mfma_f32_16x16x32_bf16 v[8:11], v[22:25], v[102:105], v[8:11]
	v_mfma_f32_16x16x32_bf16 v[14:17], v[30:33], v[102:105], v[14:17]
	v_mfma_f32_16x16x32_bf16 v[62:65], v[18:21], v[106:109], 0
	v_mfma_f32_16x16x32_bf16 v[102:105], v[26:29], v[106:109], 0
	v_mfma_f32_16x16x32_bf16 v[106:109], v[18:21], v[114:117], 0
	v_mfma_f32_16x16x32_bf16 v[18:21], v[18:21], v[122:125], 0
	v_mfma_f32_16x16x32_bf16 v[62:65], v[22:25], v[110:113], v[62:65]
	v_mfma_f32_16x16x32_bf16 v[102:105], v[30:33], v[110:113], v[102:105]
	v_mfma_f32_16x16x32_bf16 v[106:109], v[22:25], v[118:121], v[106:109]
	v_mfma_f32_16x16x32_bf16 v[110:113], v[26:29], v[114:117], 0
	v_mfma_f32_16x16x32_bf16 v[18:21], v[22:25], v[126:129], v[18:21]
	v_mfma_f32_16x16x32_bf16 v[22:25], v[26:29], v[122:125], 0
	v_mfma_f32_16x16x32_bf16 v[110:113], v[30:33], v[118:121], v[110:113]
	v_mfma_f32_16x16x32_bf16 v[22:25], v[30:33], v[126:129], v[22:25]
	s_setprio 0
	s_barrier
	s_add_i32 s46, 0, 0x18000
	s_add_i32 s52, 0, 0x1c000
	v_add_u32_e32 v222, s46, v161
	v_add_u32_e32 v223, s52, v161
	ds_read_b128 v[26:29], v222
	ds_read_b128 v[30:33], v222 offset:1024
	ds_read_b128 v[114:117], v222 offset:2048
	ds_read_b128 v[118:121], v222 offset:3072
	ds_read_b128 v[182:185], v162 offset:32768
	ds_read_b128 v[186:189], v162 offset:33792
	ds_read_b128 v[190:193], v162 offset:34816
	ds_read_b128 v[194:197], v162 offset:35840
	ds_read_b128 v[198:201], v162 offset:36864
	ds_read_b128 v[202:205], v162 offset:37888
	ds_read_b128 v[206:209], v162 offset:38912
	ds_read_b128 v[210:213], v162 offset:39936
	ds_read_b128 v[122:125], v223
	ds_read_b128 v[126:129], v223 offset:1024
	ds_read_b128 v[168:171], v223 offset:2048
	ds_read_b128 v[178:181], v223 offset:3072
	s_add_u32 s48, s26, 0xc0100
	s_addc_u32 s49, s27, 0
	s_mov_b32 m0, s41
	v_lshl_add_u64 v[216:217], s[48:49], 0, v[152:153]
	global_load_lds_dwordx4 v[216:217], off
	v_lshl_add_u64 v[216:217], s[48:49], 0, v[148:149]
	s_mov_b32 m0, s42
	s_nop 0
	global_load_lds_dwordx4 v[216:217], off
	s_waitcnt vmcnt(8)
	s_cmp_lg_u64 s[6:7], 0
	s_cbranch_scc1 .Lpp_lead_2
	s_waitcnt lgkmcnt(0)
.Lpp_lead_2:
	s_waitcnt lgkmcnt(4)
	s_barrier
	s_setprio 1
	s_waitcnt lgkmcnt(4)
	v_mfma_f32_16x16x32_bf16 v[66:69], v[26:29], v[182:185], v[66:69]
	v_mfma_f32_16x16x32_bf16 v[70:73], v[114:117], v[182:185], v[70:73]
	v_mfma_f32_16x16x32_bf16 v[74:77], v[26:29], v[190:193], v[74:77]
	v_mfma_f32_16x16x32_bf16 v[78:81], v[114:117], v[190:193], v[78:81]
	v_mfma_f32_16x16x32_bf16 v[82:85], v[26:29], v[198:201], v[82:85]
	v_mfma_f32_16x16x32_bf16 v[86:89], v[114:117], v[198:201], v[86:89]
	v_mfma_f32_16x16x32_bf16 v[90:93], v[26:29], v[206:209], v[90:93]
	v_mfma_f32_16x16x32_bf16 v[94:97], v[114:117], v[206:209], v[94:97]
	v_mfma_f32_16x16x32_bf16 v[66:69], v[30:33], v[186:189], v[66:69]
	v_mfma_f32_16x16x32_bf16 v[70:73], v[118:121], v[186:189], v[70:73]
	v_mfma_f32_16x16x32_bf16 v[74:77], v[30:33], v[194:197], v[74:77]
	v_mfma_f32_16x16x32_bf16 v[78:81], v[118:121], v[194:197], v[78:81]
	v_mfma_f32_16x16x32_bf16 v[82:85], v[30:33], v[202:205], v[82:85]
	v_mfma_f32_16x16x32_bf16 v[86:89], v[118:121], v[202:205], v[86:89]
	v_mfma_f32_16x16x32_bf16 v[90:93], v[30:33], v[210:213], v[90:93]
	v_mfma_f32_16x16x32_bf16 v[94:97], v[118:121], v[210:213], v[94:97]
	s_setprio 0
	s_setprio 1
	s_waitcnt lgkmcnt(0)
	v_mfma_f32_16x16x32_bf16 v[98:101], v[122:125], v[182:185], v[98:101]
	v_mfma_f32_16x16x32_bf16 v[34:37], v[168:171], v[182:185], v[34:37]
	v_mfma_f32_16x16x32_bf16 v[38:41], v[122:125], v[190:193], v[38:41]
	v_mfma_f32_16x16x32_bf16 v[42:45], v[168:171], v[190:193], v[42:45]
	v_mfma_f32_16x16x32_bf16 v[46:49], v[122:125], v[198:201], v[46:49]
	v_mfma_f32_16x16x32_bf16 v[50:53], v[168:171], v[198:201], v[50:53]
	v_mfma_f32_16x16x32_bf16 v[54:57], v[122:125], v[206:209], v[54:57]
	v_mfma_f32_16x16x32_bf16 v[58:61], v[168:171], v[206:209], v[58:61]
	v_mfma_f32_16x16x32_bf16 v[98:101], v[126:129], v[186:189], v[98:101]
	v_mfma_f32_16x16x32_bf16 v[34:37], v[178:181], v[186:189], v[34:37]
	v_mfma_f32_16x16x32_bf16 v[38:41], v[126:129], v[194:197], v[38:41]
	v_mfma_f32_16x16x32_bf16 v[42:45], v[178:181], v[194:197], v[42:45]
	v_mfma_f32_16x16x32_bf16 v[46:49], v[126:129], v[202:205], v[46:49]
	v_mfma_f32_16x16x32_bf16 v[50:53], v[178:181], v[202:205], v[50:53]
	v_mfma_f32_16x16x32_bf16 v[54:57], v[126:129], v[210:213], v[54:57]
	v_mfma_f32_16x16x32_bf16 v[58:61], v[178:181], v[210:213], v[58:61]
	s_setprio 0
	s_barrier
; #define PG8_STAGE(bufoff, gbase, voff) do { _Pragma("unroll") for (int _i = 0; _i < 2; ++_i) \
;         __builtin_amdgcn_global_load_lds((const unsigned*)((const char*)(gbase) + (voff)[_i]), (LAS unsigned*)(lds + (bufoff) + ldsw + _i * 8192), 16, 0, 0); } while (0)
; #define PG8_LDA(dst, b, h) do { _Pragma("unroll") for (int m = 0; m < 4; ++m) _Pragma("unroll") for (int k = 0; k < 2; ++k) dst[m][k] = *(const LAS bf16x8*)(lds + PG8_SA(b, h) + aoff + m * 2048 + k * 1024); } while (0)
; #define PG8_LDB(dst, b, h) do { _Pragma("unroll") for (int n = 0; n < 2; ++n) _Pragma("unroll") for (int k = 0; k < 2; ++k) dst[n][k] = *(const LAS bf16x8*)(lds + PG8_SB(b, h) + boff + n * 2048 + k * 1024); } while (0)
; #define PG8_MMA(ai, bj, At, Bt) do { __builtin_amdgcn_s_setprio(1); _Pragma("unroll") for (int m = 0; m < 4; ++m) _Pragma("unroll") for (int n = 0; n < 2; ++n) _Pragma("unroll") for (int k = 0; k < 2; ++k) \
;         acc[ai][bj][m][n] = __builtin_amdgcn_mfma_f32_16x16x32_bf16(Bt[n][k], At[m][k], acc[ai][bj][m][n], 0, 0, 0); __builtin_amdgcn_s_setprio(0); } while (0)
; #define PG8_WAIT_V(n) asm volatile("s_waitcnt vmcnt(" #n ")" ::: "memory")
; #define PG8_BAR __builtin_amdgcn_s_barrier()
; template <class Epi>
; __device__ __forceinline__ void gemm_phase(LAS unsigned char* lds, const Gemm g, const StaticOrder& S, const Epi& E, int wave_s) {
;     ...
;             PG8_LDB(B0, 0, 0); PG8_LDB(B1, 0, 1); PG8_SCHED; PG8_LDA(At, 0, 0); PG8_STAGE(PG8_SA(1, 1), a1 + hstepA, voffA);
;             PG8_WAIT_V(8); PG8_WAIT_L(0); PG8_BAR; PG8_MMA(0, 0, At, B0); PG8_MMA(0, 1, At, B1); PG8_BAR; PG8_SCHED;
;             PG8_LDA(At, 0, 1); PG8_STAGE(PG8_SB(0, 0), b2, voffB); PG8_STAGE(PG8_SB(0, 1), b2 + hstepB, voffB); PG8_STAGE(PG8_SA(0, 0), a2, voffA);
;             PG8_WAIT_V(8); PG8_WAIT_L(0); PG8_BAR; PG8_MMA(1, 0, At, B0); PG8_MMA(1, 1, At, B1); PG8_BAR; PG8_SCHED;
;             PG8_LDB(B0, 1, 0); PG8_LDB(B1, 1, 1); PG8_SCHED; PG8_LDA(At, 1, 0); PG8_STAGE(PG8_SA(0, 1), a2 + hstepA, voffA);
;             PG8_WAIT_V(8); PG8_WAIT_L(0); PG8_BAR; PG8_MMA(0, 0, At, B0); PG8_MMA(0, 1, At, B1); PG8_BAR; PG8_SCHED;
;             PG8_LDA(At, 1, 1); PG8_STAGE(PG8_SB(1, 0), b3, voffB); PG8_STAGE(PG8_SB(1, 1), b3 + hstepB, voffB); PG8_STAGE(PG8_SA(1, 0), a3, voffA);
;             PG8_WAIT_V(8); PG8_WAIT_L(0); PG8_BAR; PG8_MMA(1, 0, At, B0); PG8_MMA(1, 1, At, B1); PG8_BAR; PG8_SCHED;
	s_add_i32 s48, s46, s30
	s_add_i32 s46, s48, 0x2000
	v_lshl_add_u64 v[172:173], v[172:173], 0, s[64:65]
	s_mov_b32 m0, s48
	s_add_u32 s50, s22, 0x10180
	ds_read_b128 v[182:185], v162 offset:49152
	ds_read_b128 v[186:189], v162 offset:50176
	ds_read_b128 v[190:193], v162 offset:51200
	ds_read_b128 v[194:197], v162 offset:52224
	ds_read_b128 v[198:201], v162 offset:53248
	ds_read_b128 v[202:205], v162 offset:54272
	ds_read_b128 v[206:209], v162 offset:55296
	ds_read_b128 v[210:213], v162 offset:56320
	global_load_lds_dwordx4 v[172:173], off
	v_lshl_add_u64 v[172:173], v[174:175], 0, s[64:65]
	s_mov_b32 m0, s46
	s_addc_u32 s51, s23, 0
	s_add_i32 s22, s52, s30
	global_load_lds_dwordx4 v[172:173], off
	v_lshl_add_u64 v[172:173], s[50:51], 0, v[150:151]
	s_mov_b32 m0, s22
	s_add_i32 s23, s22, 0x2000
	global_load_lds_dwordx4 v[172:173], off
	v_lshl_add_u64 v[172:173], s[50:51], 0, v[146:147]
	s_mov_b32 m0, s23
	s_nop 0
	global_load_lds_dwordx4 v[172:173], off
	v_lshl_add_u64 v[172:173], v[176:177], 0, s[64:65]
	s_mov_b32 m0, s43
	s_nop 0
	global_load_lds_dwordx4 v[172:173], off
	v_lshl_add_u64 v[172:173], v[214:215], 0, s[64:65]
	s_mov_b32 m0, s69
	s_nop 0
	global_load_lds_dwordx4 v[172:173], off
	s_waitcnt vmcnt(8)
	s_waitcnt lgkmcnt(0)
	s_barrier
	s_setprio 1
	s_waitcnt lgkmcnt(0)
	v_mfma_f32_16x16x32_bf16 v[0:3], v[26:29], v[206:209], v[0:3]
	v_mfma_f32_16x16x32_bf16 v[4:7], v[114:117], v[206:209], v[4:7]
	v_mfma_f32_16x16x32_bf16 v[130:133], v[26:29], v[182:185], v[130:133]
	v_mfma_f32_16x16x32_bf16 v[134:137], v[114:117], v[182:185], v[134:137]
	v_mfma_f32_16x16x32_bf16 v[138:141], v[26:29], v[190:193], v[138:141]
	v_mfma_f32_16x16x32_bf16 v[142:145], v[114:117], v[190:193], v[142:145]
	v_mfma_f32_16x16x32_bf16 v[156:159], v[26:29], v[198:201], v[156:159]
	v_mfma_f32_16x16x32_bf16 v[164:167], v[114:117], v[198:201], v[164:167]
	v_mfma_f32_16x16x32_bf16 v[0:3], v[30:33], v[210:213], v[0:3]
	v_mfma_f32_16x16x32_bf16 v[4:7], v[118:121], v[210:213], v[4:7]
	v_mfma_f32_16x16x32_bf16 v[130:133], v[30:33], v[186:189], v[130:133]
	v_mfma_f32_16x16x32_bf16 v[134:137], v[118:121], v[186:189], v[134:137]
	v_mfma_f32_16x16x32_bf16 v[138:141], v[30:33], v[194:197], v[138:141]
	v_mfma_f32_16x16x32_bf16 v[142:145], v[118:121], v[194:197], v[142:145]
	v_mfma_f32_16x16x32_bf16 v[156:159], v[30:33], v[202:205], v[156:159]
	v_mfma_f32_16x16x32_bf16 v[164:167], v[118:121], v[202:205], v[164:167]
	s_setprio 0
	s_setprio 1
	v_mfma_f32_16x16x32_bf16 v[8:11], v[122:125], v[182:185], v[8:11]
	v_mfma_f32_16x16x32_bf16 v[14:17], v[168:171], v[182:185], v[14:17]
	v_mfma_f32_16x16x32_bf16 v[26:29], v[122:125], v[190:193], v[62:65]
	v_mfma_f32_16x16x32_bf16 v[30:33], v[168:171], v[190:193], v[102:105]
	v_mfma_f32_16x16x32_bf16 v[62:65], v[122:125], v[198:201], v[106:109]
	v_mfma_f32_16x16x32_bf16 v[102:105], v[168:171], v[198:201], v[110:113]
	v_mfma_f32_16x16x32_bf16 v[18:21], v[122:125], v[206:209], v[18:21]
	v_mfma_f32_16x16x32_bf16 v[22:25], v[168:171], v[206:209], v[22:25]
	v_mfma_f32_16x16x32_bf16 v[8:11], v[126:129], v[186:189], v[8:11]
	v_mfma_f32_16x16x32_bf16 v[14:17], v[178:181], v[186:189], v[14:17]
	v_mfma_f32_16x16x32_bf16 v[26:29], v[126:129], v[194:197], v[26:29]
	v_mfma_f32_16x16x32_bf16 v[30:33], v[178:181], v[194:197], v[30:33]
	v_mfma_f32_16x16x32_bf16 v[62:65], v[126:129], v[202:205], v[62:65]
	v_mfma_f32_16x16x32_bf16 v[102:105], v[178:181], v[202:205], v[102:105]
	v_mfma_f32_16x16x32_bf16 v[18:21], v[126:129], v[210:213], v[18:21]
	v_mfma_f32_16x16x32_bf16 v[22:25], v[178:181], v[210:213], v[22:25]
	s_setprio 0
	s_barrier
	ds_read_b128 v[106:109], v163
	ds_read_b128 v[110:113], v163 offset:1024
	ds_read_b128 v[114:117], v163 offset:2048
	ds_read_b128 v[118:121], v163 offset:3072
	ds_read_b128 v[182:185], v162
	ds_read_b128 v[186:189], v162 offset:1024
	ds_read_b128 v[190:193], v162 offset:2048
	ds_read_b128 v[194:197], v162 offset:3072
	ds_read_b128 v[198:201], v162 offset:4096
	ds_read_b128 v[202:205], v162 offset:5120
	ds_read_b128 v[206:209], v162 offset:6144
	ds_read_b128 v[210:213], v162 offset:7168
	ds_read_b128 v[122:125], v218
	ds_read_b128 v[126:129], v218 offset:1024
	ds_read_b128 v[168:171], v218 offset:2048
	ds_read_b128 v[178:181], v218 offset:3072
	s_add_u32 s26, s26, 0xc0180
	s_addc_u32 s27, s27, 0
	s_mov_b32 m0, s47
	v_lshl_add_u64 v[172:173], s[26:27], 0, v[152:153]
	global_load_lds_dwordx4 v[172:173], off
	v_lshl_add_u64 v[172:173], s[26:27], 0, v[148:149]
	s_mov_b32 m0, s11
	s_nop 0
	global_load_lds_dwordx4 v[172:173], off
	s_waitcnt vmcnt(8)
	s_cmp_lg_u64 s[6:7], 0
	s_cbranch_scc1 .Lpp_lead_3
	s_waitcnt lgkmcnt(0)
; #define PG8_STAGE(bufoff, gbase, voff) do { _Pragma("unroll") for (int _i = 0; _i < 2; ++_i) \
;         __builtin_amdgcn_global_load_lds((const unsigned*)((const char*)(gbase) + (voff)[_i]), (LAS unsigned*)(lds + (bufoff) + ldsw + _i * 8192), 16, 0, 0); } while (0)
; #define PG8_LDA(dst, b, h) do { _Pragma("unroll") for (int m = 0; m < 4; ++m) _Pragma("unroll") for (int k = 0; k < 2; ++k) dst[m][k] = *(const LAS bf16x8*)(lds + PG8_SA(b, h) + aoff + m * 2048 + k * 1024); } while (0)
; #define PG8_LDB(dst, b, h) do { _Pragma("unroll") for (int n = 0; n < 2; ++n) _Pragma("unroll") for (int k = 0; k < 2; ++k) dst[n][k] = *(const LAS bf16x8*)(lds + PG8_SB(b, h) + boff + n * 2048 + k * 1024); } while (0)
; #define PG8_MMA(ai, bj, At, Bt) do { __builtin_amdgcn_s_setprio(1); _Pragma("unroll") for (int m = 0; m < 4; ++m) _Pragma("unroll") for (int n = 0; n < 2; ++n) _Pragma("unroll") for (int k = 0; k < 2; ++k) \
;         acc[ai][bj][m][n] = __builtin_amdgcn_mfma_f32_16x16x32_bf16(Bt[n][k], At[m][k], acc[ai][bj][m][n], 0, 0, 0); __builtin_amdgcn_s_setprio(0); } while (0)
; #define PG8_WAIT_V(n) asm volatile("s_waitcnt vmcnt(" #n ")" ::: "memory")
; #define PG8_WAIT_L(n) asm volatile("s_waitcnt lgkmcnt(" #n ")" ::: "memory")
; #define PG8_BAR __builtin_amdgcn_s_barrier()
; #define PG8_SCHED __builtin_amdgcn_sched_barrier(0)
; template <class Epi>
; __device__ __forceinline__ void gemm_phase(LAS unsigned char* lds, const Gemm g, const StaticOrder& S, const Epi& E, int wave_s) {
;     ...
;             PG8_WAIT_V(8); PG8_WAIT_L(0); PG8_BAR; PG8_MMA(0, 0, At, B0); PG8_MMA(0, 1, At, B1); PG8_BAR; PG8_SCHED;
;             PG8_LDA(At, 0, 1); PG8_STAGE(PG8_SB(0, 0), b2, voffB); PG8_STAGE(PG8_SB(0, 1), b2 + hstepB, voffB); PG8_STAGE(PG8_SA(0, 0), a2, voffA);
;             PG8_WAIT_V(8); PG8_WAIT_L(0); PG8_BAR; PG8_MMA(1, 0, At, B0); PG8_MMA(1, 1, At, B1); PG8_BAR; PG8_SCHED;
;             PG8_LDB(B0, 1, 0); PG8_LDB(B1, 1, 1); PG8_SCHED; PG8_LDA(At, 1, 0); PG8_STAGE(PG8_SA(0, 1), a2 + hstepA, voffA);
;             PG8_WAIT_V(8); PG8_WAIT_L(0); PG8_BAR; PG8_MMA(0, 0, At, B0); PG8_MMA(0, 1, At, B1); PG8_BAR; PG8_SCHED;
.Lpp_lead_3:
	s_waitcnt lgkmcnt(4)
	s_barrier
	s_setprio 1
	s_waitcnt lgkmcnt(4)
	v_mfma_f32_16x16x32_bf16 v[90:93], v[106:109], v[206:209], v[90:93]
	v_mfma_f32_16x16x32_bf16 v[66:69], v[106:109], v[182:185], v[66:69]
	v_mfma_f32_16x16x32_bf16 v[70:73], v[114:117], v[182:185], v[70:73]
	v_mfma_f32_16x16x32_bf16 v[74:77], v[106:109], v[190:193], v[74:77]
	v_mfma_f32_16x16x32_bf16 v[78:81], v[114:117], v[190:193], v[78:81]
	v_mfma_f32_16x16x32_bf16 v[82:85], v[106:109], v[198:201], v[82:85]
	v_mfma_f32_16x16x32_bf16 v[86:89], v[114:117], v[198:201], v[86:89]
	v_mfma_f32_16x16x32_bf16 v[214:217], v[110:113], v[210:213], v[90:93]
	v_mfma_f32_16x16x32_bf16 v[90:93], v[114:117], v[206:209], v[94:97]
	v_mfma_f32_16x16x32_bf16 v[66:69], v[110:113], v[186:189], v[66:69]
	v_mfma_f32_16x16x32_bf16 v[70:73], v[118:121], v[186:189], v[70:73]
	v_mfma_f32_16x16x32_bf16 v[74:77], v[110:113], v[194:197], v[74:77]
	v_mfma_f32_16x16x32_bf16 v[78:81], v[118:121], v[194:197], v[78:81]
	v_mfma_f32_16x16x32_bf16 v[82:85], v[110:113], v[202:205], v[82:85]
	v_mfma_f32_16x16x32_bf16 v[86:89], v[118:121], v[202:205], v[86:89]
	v_mfma_f32_16x16x32_bf16 v[94:97], v[118:121], v[210:213], v[90:93]
	s_setprio 0
	s_setprio 1
	s_waitcnt lgkmcnt(0)
	v_mfma_f32_16x16x32_bf16 v[34:37], v[168:171], v[182:185], v[34:37]
	v_mfma_f32_16x16x32_bf16 v[38:41], v[122:125], v[190:193], v[38:41]
	v_mfma_f32_16x16x32_bf16 v[42:45], v[168:171], v[190:193], v[42:45]
	v_mfma_f32_16x16x32_bf16 v[46:49], v[122:125], v[198:201], v[46:49]
	v_mfma_f32_16x16x32_bf16 v[50:53], v[168:171], v[198:201], v[50:53]
	v_mfma_f32_16x16x32_bf16 v[54:57], v[122:125], v[206:209], v[54:57]
	v_mfma_f32_16x16x32_bf16 v[58:61], v[168:171], v[206:209], v[58:61]
	v_mfma_f32_16x16x32_bf16 v[90:93], v[122:125], v[182:185], v[98:101]
	v_mfma_f32_16x16x32_bf16 v[34:37], v[178:181], v[186:189], v[34:37]
	v_mfma_f32_16x16x32_bf16 v[38:41], v[126:129], v[194:197], v[38:41]
	v_mfma_f32_16x16x32_bf16 v[42:45], v[178:181], v[194:197], v[42:45]
	v_mfma_f32_16x16x32_bf16 v[46:49], v[126:129], v[202:205], v[46:49]
	v_mfma_f32_16x16x32_bf16 v[50:53], v[178:181], v[202:205], v[50:53]
	v_mfma_f32_16x16x32_bf16 v[54:57], v[126:129], v[210:213], v[54:57]
	v_mfma_f32_16x16x32_bf16 v[58:61], v[178:181], v[210:213], v[58:61]
	v_mfma_f32_16x16x32_bf16 v[218:221], v[126:129], v[186:189], v[90:93]
	s_setprio 0
	s_barrier
	s_mov_b32 m0, s45
	v_lshl_add_u64 v[176:177], s[2:3], 0, v[150:151]
	s_add_u32 s26, s2, 0x10000
	ds_read_b128 v[90:93], v162 offset:16384
	ds_read_b128 v[98:101], v162 offset:17408
	ds_read_b128 v[182:185], v162 offset:18432
	ds_read_b128 v[186:189], v162 offset:19456
	ds_read_b128 v[190:193], v162 offset:20480
	ds_read_b128 v[194:197], v162 offset:21504
	ds_read_b128 v[198:201], v162 offset:22528
	ds_read_b128 v[202:205], v162 offset:23552
	global_load_lds_dwordx4 v[176:177], off
	v_lshl_add_u64 v[234:235], s[2:3], 0, v[146:147]
	s_mov_b32 m0, s36
	s_addc_u32 s27, s3, 0
	global_load_lds_dwordx4 v[234:235], off
	v_lshl_add_u64 v[172:173], s[26:27], 0, v[150:151]
	s_mov_b32 m0, s37
	v_lshl_add_u64 v[240:241], s[12:13], 0, v[152:153]
	global_load_lds_dwordx4 v[172:173], off
	v_lshl_add_u64 v[172:173], s[26:27], 0, v[146:147]
	s_mov_b32 m0, s44
	v_lshl_add_u64 v[250:251], s[12:13], 0, v[148:149]
	global_load_lds_dwordx4 v[172:173], off
	s_mov_b32 m0, s31
	s_nop 0
	global_load_lds_dwordx4 v[240:241], off
	s_mov_b32 m0, s40
	s_nop 0
	global_load_lds_dwordx4 v[250:251], off
	s_waitcnt vmcnt(8)
	s_waitcnt lgkmcnt(0)
	s_barrier
	s_setprio 1
	s_waitcnt lgkmcnt(0)
	v_mfma_f32_16x16x32_bf16 v[0:3], v[106:109], v[198:201], v[0:3]
	v_mfma_f32_16x16x32_bf16 v[4:7], v[114:117], v[198:201], v[4:7]
	v_mfma_f32_16x16x32_bf16 v[130:133], v[106:109], v[90:93], v[130:133]
	v_mfma_f32_16x16x32_bf16 v[134:137], v[114:117], v[90:93], v[134:137]
	v_mfma_f32_16x16x32_bf16 v[138:141], v[106:109], v[182:185], v[138:141]
	v_mfma_f32_16x16x32_bf16 v[142:145], v[114:117], v[182:185], v[142:145]
	v_mfma_f32_16x16x32_bf16 v[156:159], v[106:109], v[190:193], v[156:159]
	v_mfma_f32_16x16x32_bf16 v[164:167], v[114:117], v[190:193], v[164:167]
	v_mfma_f32_16x16x32_bf16 v[0:3], v[110:113], v[202:205], v[0:3]
	v_mfma_f32_16x16x32_bf16 v[4:7], v[118:121], v[202:205], v[4:7]
	v_mfma_f32_16x16x32_bf16 v[130:133], v[110:113], v[98:101], v[130:133]
	v_mfma_f32_16x16x32_bf16 v[134:137], v[118:121], v[98:101], v[134:137]
	v_mfma_f32_16x16x32_bf16 v[138:141], v[110:113], v[186:189], v[138:141]
	v_mfma_f32_16x16x32_bf16 v[142:145], v[118:121], v[186:189], v[142:145]
	v_mfma_f32_16x16x32_bf16 v[156:159], v[110:113], v[194:197], v[156:159]
	v_mfma_f32_16x16x32_bf16 v[164:167], v[118:121], v[194:197], v[164:167]
	s_setprio 0
	s_setprio 1
	v_mfma_f32_16x16x32_bf16 v[8:11], v[122:125], v[90:93], v[8:11]
	v_mfma_f32_16x16x32_bf16 v[206:209], v[126:129], v[98:101], v[8:11]
	v_mfma_f32_16x16x32_bf16 v[8:11], v[168:171], v[90:93], v[14:17]
	v_mfma_f32_16x16x32_bf16 v[14:17], v[178:181], v[98:101], v[8:11]
	v_mfma_f32_16x16x32_bf16 v[8:11], v[122:125], v[182:185], v[26:29]
	v_mfma_f32_16x16x32_bf16 v[210:213], v[126:129], v[186:189], v[8:11]
	v_mfma_f32_16x16x32_bf16 v[8:11], v[168:171], v[182:185], v[30:33]
	v_mfma_f32_16x16x32_bf16 v[30:33], v[178:181], v[186:189], v[8:11]
	v_mfma_f32_16x16x32_bf16 v[8:11], v[122:125], v[190:193], v[62:65]
	v_mfma_f32_16x16x32_bf16 v[182:185], v[126:129], v[194:197], v[8:11]
	v_mfma_f32_16x16x32_bf16 v[8:11], v[168:171], v[190:193], v[102:105]
	v_mfma_f32_16x16x32_bf16 v[186:189], v[178:181], v[194:197], v[8:11]
	v_mfma_f32_16x16x32_bf16 v[8:11], v[122:125], v[198:201], v[18:21]
	v_mfma_f32_16x16x32_bf16 v[190:193], v[126:129], v[202:205], v[8:11]
	v_mfma_f32_16x16x32_bf16 v[8:11], v[168:171], v[198:201], v[22:25]
	v_mfma_f32_16x16x32_bf16 v[168:171], v[178:181], v[202:205], v[8:11]
	s_setprio 0
	s_barrier
	s_nop 4
	ds_read_b128 v[8:11], v222
	ds_read_b128 v[22:25], v222 offset:1024
	ds_read_b128 v[62:65], v222 offset:2048
	ds_read_b128 v[178:181], v222 offset:3072
	ds_read_b128 v[18:21], v162 offset:32768
	ds_read_b128 v[26:29], v162 offset:33792
	ds_read_b128 v[102:105], v162 offset:34816
	ds_read_b128 v[226:229], v162 offset:35840
	ds_read_b128 v[230:233], v162 offset:36864
	ds_read_b128 v[242:245], v162 offset:37888
	ds_read_b128 v[246:249], v162 offset:38912
	ds_read_b128 v[172:175], v162 offset:39936
	ds_read_b128 v[194:197], v223
	ds_read_b128 v[198:201], v223 offset:1024
	ds_read_b128 v[202:205], v223 offset:2048
	ds_read_b128 v[222:225], v223 offset:3072
	s_add_u32 s26, s12, 0xc0000
	s_addc_u32 s27, s13, 0
	s_mov_b32 m0, s41
	v_lshl_add_u64 v[90:91], s[26:27], 0, v[152:153]
	global_load_lds_dwordx4 v[90:91], off
	v_lshl_add_u64 v[90:91], s[26:27], 0, v[148:149]
	s_mov_b32 m0, s42
	s_nop 0
	global_load_lds_dwordx4 v[90:91], off
	s_waitcnt vmcnt(8)
	s_cmp_lg_u64 s[6:7], 0
	s_cbranch_scc1 .Lpp_lead_4
	s_waitcnt lgkmcnt(0)
; #define PG8_STAGE(bufoff, gbase, voff) do { _Pragma("unroll") for (int _i = 0; _i < 2; ++_i) \
;         __builtin_amdgcn_global_load_lds((const unsigned*)((const char*)(gbase) + (voff)[_i]), (LAS unsigned*)(lds + (bufoff) + ldsw + _i * 8192), 16, 0, 0); } while (0)
; #define PG8_LDA(dst, b, h) do { _Pragma("unroll") for (int m = 0; m < 4; ++m) _Pragma("unroll") for (int k = 0; k < 2; ++k) dst[m][k] = *(const LAS bf16x8*)(lds + PG8_SA(b, h) + aoff + m * 2048 + k * 1024); } while (0)
; #define PG8_MMA(ai, bj, At, Bt) do { __builtin_amdgcn_s_setprio(1); _Pragma("unroll") for (int m = 0; m < 4; ++m) _Pragma("unroll") for (int n = 0; n < 2; ++n) _Pragma("unroll") for (int k = 0; k < 2; ++k) \
;         acc[ai][bj][m][n] = __builtin_amdgcn_mfma_f32_16x16x32_bf16(Bt[n][k], At[m][k], acc[ai][bj][m][n], 0, 0, 0); __builtin_amdgcn_s_setprio(0); } while (0)
; #define PG8_WAIT_V(n) asm volatile("s_waitcnt vmcnt(" #n ")" ::: "memory")
; #define PG8_WAIT_L(n) asm volatile("s_waitcnt lgkmcnt(" #n ")" ::: "memory")
; #define PG8_BAR __builtin_amdgcn_s_barrier()
; #define PG8_SCHED __builtin_amdgcn_sched_barrier(0)
; template <class Epi>
; __device__ __forceinline__ void gemm_phase(LAS unsigned char* lds, const Gemm g, const StaticOrder& S, const Epi& E, int wave_s) {
;     ...
;             PG8_WAIT_V(8); PG8_WAIT_L(0); PG8_BAR; PG8_MMA(0, 0, At, B0); PG8_MMA(0, 1, At, B1); PG8_BAR; PG8_SCHED;
;             PG8_LDA(At, 1, 1); PG8_STAGE(PG8_SB(1, 0), b3, voffB); PG8_STAGE(PG8_SB(1, 1), b3 + hstepB, voffB); PG8_STAGE(PG8_SA(1, 0), a3, voffA);
;             PG8_WAIT_V(8); PG8_WAIT_L(0); PG8_BAR; PG8_MMA(1, 0, At, B0); PG8_MMA(1, 1, At, B1); PG8_BAR; PG8_SCHED;
;         }
;         if (wr == 0) PG8_BAR;
.Lpp_lead_4:
	s_waitcnt lgkmcnt(4)
	s_barrier
	s_setprio 1
	s_waitcnt lgkmcnt(4)
	v_mfma_f32_16x16x32_bf16 v[66:69], v[8:11], v[18:21], v[66:69]
	v_mfma_f32_16x16x32_bf16 v[122:125], v[22:25], v[26:29], v[66:69]
	v_mfma_f32_16x16x32_bf16 v[66:69], v[62:65], v[18:21], v[70:73]
	v_mfma_f32_16x16x32_bf16 v[114:117], v[178:181], v[26:29], v[66:69]
	v_mfma_f32_16x16x32_bf16 v[66:69], v[8:11], v[102:105], v[74:77]
	v_mfma_f32_16x16x32_bf16 v[106:109], v[22:25], v[226:229], v[66:69]
	v_mfma_f32_16x16x32_bf16 v[66:69], v[62:65], v[102:105], v[78:81]
	v_mfma_f32_16x16x32_bf16 v[98:101], v[178:181], v[226:229], v[66:69]
	v_mfma_f32_16x16x32_bf16 v[66:69], v[8:11], v[230:233], v[82:85]
	v_mfma_f32_16x16x32_bf16 v[90:93], v[22:25], v[242:245], v[66:69]
	v_mfma_f32_16x16x32_bf16 v[66:69], v[62:65], v[230:233], v[86:89]
	v_mfma_f32_16x16x32_bf16 v[82:85], v[178:181], v[242:245], v[66:69]
	v_mfma_f32_16x16x32_bf16 v[66:69], v[8:11], v[246:249], v[214:217]
	v_mfma_f32_16x16x32_bf16 v[74:77], v[22:25], v[172:175], v[66:69]
	v_mfma_f32_16x16x32_bf16 v[66:69], v[62:65], v[246:249], v[94:97]
	v_mfma_f32_16x16x32_bf16 v[66:69], v[178:181], v[172:175], v[66:69]
	s_setprio 0
	s_setprio 1
	s_waitcnt lgkmcnt(0)
	v_mfma_f32_16x16x32_bf16 v[70:73], v[194:197], v[18:21], v[218:221]
	v_mfma_f32_16x16x32_bf16 v[18:21], v[202:205], v[18:21], v[34:37]
	v_mfma_f32_16x16x32_bf16 v[118:121], v[222:225], v[26:29], v[18:21]
	v_mfma_f32_16x16x32_bf16 v[18:21], v[194:197], v[102:105], v[38:41]
	v_mfma_f32_16x16x32_bf16 v[110:113], v[198:201], v[226:229], v[18:21]
	v_mfma_f32_16x16x32_bf16 v[18:21], v[202:205], v[102:105], v[42:45]
	v_mfma_f32_16x16x32_bf16 v[102:105], v[222:225], v[226:229], v[18:21]
	v_mfma_f32_16x16x32_bf16 v[18:21], v[194:197], v[230:233], v[46:49]
	v_mfma_f32_16x16x32_bf16 v[94:97], v[198:201], v[242:245], v[18:21]
	v_mfma_f32_16x16x32_bf16 v[18:21], v[202:205], v[230:233], v[50:53]
	v_mfma_f32_16x16x32_bf16 v[86:89], v[222:225], v[242:245], v[18:21]
	v_mfma_f32_16x16x32_bf16 v[18:21], v[194:197], v[246:249], v[54:57]
	v_mfma_f32_16x16x32_bf16 v[78:81], v[198:201], v[172:175], v[18:21]
	v_mfma_f32_16x16x32_bf16 v[18:21], v[202:205], v[246:249], v[58:61]
	v_mfma_f32_16x16x32_bf16 v[126:129], v[198:201], v[26:29], v[70:73]
	v_mfma_f32_16x16x32_bf16 v[70:73], v[222:225], v[172:175], v[18:21]
	s_setprio 0
	s_barrier
	s_mov_b32 m0, s48
	s_nop 2
	v_lshl_add_u64 v[18:19], v[176:177], 0, s[84:85]
	s_add_u32 s2, s2, 0x10080
	ds_read_b128 v[38:41], v162 offset:49152
	ds_read_b128 v[46:49], v162 offset:50176
	ds_read_b128 v[172:175], v162 offset:51200
	ds_read_b128 v[214:217], v162 offset:52224
	ds_read_b128 v[218:221], v162 offset:53248
	ds_read_b128 v[226:229], v162 offset:54272
	ds_read_b128 v[230:233], v162 offset:55296
	ds_read_b128 v[242:245], v162 offset:56320
	global_load_lds_dwordx4 v[18:19], off
	v_lshl_add_u64 v[18:19], v[234:235], 0, s[84:85]
	s_mov_b32 m0, s46
	s_addc_u32 s3, s3, 0
	global_load_lds_dwordx4 v[18:19], off
	v_lshl_add_u64 v[18:19], s[2:3], 0, v[150:151]
	s_mov_b32 m0, s22
	s_nop 0
	global_load_lds_dwordx4 v[18:19], off
	v_lshl_add_u64 v[18:19], s[2:3], 0, v[146:147]
	s_mov_b32 m0, s23
	s_nop 0
	global_load_lds_dwordx4 v[18:19], off
	v_lshl_add_u64 v[18:19], v[240:241], 0, s[84:85]
	s_mov_b32 m0, s43
	s_nop 0
	global_load_lds_dwordx4 v[18:19], off
	v_lshl_add_u64 v[18:19], v[250:251], 0, s[84:85]
	s_mov_b32 m0, s69
	s_nop 0
	global_load_lds_dwordx4 v[18:19], off
	s_waitcnt vmcnt(8)
	s_waitcnt lgkmcnt(0)
	s_barrier
	s_setprio 1
	s_waitcnt lgkmcnt(0)
	v_mfma_f32_16x16x32_bf16 v[18:21], v[8:11], v[38:41], v[130:133]
	v_mfma_f32_16x16x32_bf16 v[58:61], v[22:25], v[46:49], v[18:21]
	v_mfma_f32_16x16x32_bf16 v[18:21], v[62:65], v[38:41], v[134:137]
	v_mfma_f32_16x16x32_bf16 v[50:53], v[178:181], v[46:49], v[18:21]
	v_mfma_f32_16x16x32_bf16 v[18:21], v[8:11], v[172:175], v[138:141]
	v_mfma_f32_16x16x32_bf16 v[42:45], v[22:25], v[214:217], v[18:21]
	v_mfma_f32_16x16x32_bf16 v[18:21], v[62:65], v[172:175], v[142:145]
	v_mfma_f32_16x16x32_bf16 v[34:37], v[178:181], v[214:217], v[18:21]
	v_mfma_f32_16x16x32_bf16 v[18:21], v[8:11], v[218:221], v[156:159]
	v_mfma_f32_16x16x32_bf16 v[0:3], v[8:11], v[230:233], v[0:3]
	v_mfma_f32_16x16x32_bf16 v[26:29], v[22:25], v[226:229], v[18:21]
	v_mfma_f32_16x16x32_bf16 v[18:21], v[62:65], v[218:221], v[164:167]
	v_mfma_f32_16x16x32_bf16 v[8:11], v[22:25], v[242:245], v[0:3]
	v_mfma_f32_16x16x32_bf16 v[0:3], v[62:65], v[230:233], v[4:7]
	v_mfma_f32_16x16x32_bf16 v[18:21], v[178:181], v[226:229], v[18:21]
	v_mfma_f32_16x16x32_bf16 v[0:3], v[178:181], v[242:245], v[0:3]
	s_setprio 0
	s_setprio 1
	v_mfma_f32_16x16x32_bf16 v[4:7], v[194:197], v[38:41], v[206:209]
	v_mfma_f32_16x16x32_bf16 v[62:65], v[198:201], v[46:49], v[4:7]
	v_mfma_f32_16x16x32_bf16 v[4:7], v[202:205], v[38:41], v[14:17]
	v_mfma_f32_16x16x32_bf16 v[54:57], v[222:225], v[46:49], v[4:7]
	v_mfma_f32_16x16x32_bf16 v[4:7], v[194:197], v[172:175], v[210:213]
	v_mfma_f32_16x16x32_bf16 v[46:49], v[198:201], v[214:217], v[4:7]
	v_mfma_f32_16x16x32_bf16 v[4:7], v[202:205], v[172:175], v[30:33]
	v_mfma_f32_16x16x32_bf16 v[38:41], v[222:225], v[214:217], v[4:7]
	v_mfma_f32_16x16x32_bf16 v[4:7], v[194:197], v[218:221], v[182:185]
	v_mfma_f32_16x16x32_bf16 v[30:33], v[198:201], v[226:229], v[4:7]
	v_mfma_f32_16x16x32_bf16 v[4:7], v[202:205], v[218:221], v[186:189]
	v_mfma_f32_16x16x32_bf16 v[22:25], v[222:225], v[226:229], v[4:7]
	v_mfma_f32_16x16x32_bf16 v[4:7], v[194:197], v[230:233], v[190:193]
	v_mfma_f32_16x16x32_bf16 v[14:17], v[198:201], v[242:245], v[4:7]
	v_mfma_f32_16x16x32_bf16 v[4:7], v[202:205], v[230:233], v[168:171]
	v_mfma_f32_16x16x32_bf16 v[4:7], v[222:225], v[242:245], v[4:7]
	s_setprio 0
	s_barrier
	s_andn2_b64 vcc, exec, s[6:7]
	s_cbranch_vccnz .LBB0_466
	s_barrier
